# in-proj phase start: the 12 serialized row-statistic load/reduce iterations unrolled so all units' loads are in flight together (plus the earlier gMLP load de-serialisation)
# baseline (speedup 1.0000x reference)
; #define LAS __attribute__((address_space(3)))
; __device__ __forceinline__ int lane_fresh() { int l; asm volatile("v_mbcnt_lo_u32_b32 %0, -1, 0\n\tv_mbcnt_hi_u32_b32 %0, -1, %0" : "=v"(l)); return l; }
; __device__ __forceinline__ float sum4(f32x4 v) { return (v[0] + v[1]) + (v[2] + v[3]); }
;     __device__ bool next(int i, Unit& u) const {
;         const long L = (long)i * G + c; if (L >= nwg) return false;
;         int wgid = (int)L; { const int q = nwg / NXCD, r = nwg % NXCD, xcd = wgid % NXCD, off = wgid / NXCD; wgid = (xcd < r ? xcd * (q + 1) : r * (q + 1) + (xcd - r) * q) + off; }
;         const int nig = WGM * nN, gid = wgid / nig, fm = gid * WGM, gsz = (nM - fm) < WGM ? (nM - fm) : WGM;
;         u.pm = fm + ((wgid % nig) % gsz); u.pn = (wgid % nig) / gsz; return true;
; template <class Sched>
; __device__ __forceinline__ void run_in_proj(LAS unsigned char* lds, const Params& p, int l, const Sched& S, int M, int rows_off, int wave, int stage_off = -1) {
;     ...
;         const int ln = lane_fresh(), t = wave * 64 + ln, r = t >> 1, hf = t & 1;
;         LAS float* rows = (LAS float*)(lds + rows_off); pg8::Unit u;
;         for (int i = 0; i < 12 && S.next(i, u); ++i) {
;             const f32x4* sp = (const f32x4*)(SSX + ((size_t)u.pm * 256 + r) * 32 + hf * 16);
;             float sm = (sum4(sp[0]) + sum4(sp[1])) + (sum4(sp[2]) + sum4(sp[3]));
;             sm += __shfl_xor(sm, 1);
;             if (hf == 0) rows[i * 256 + r] = __builtin_amdgcn_rsqf(sm * (1.0f / 2048.0f) + EPS);
;         }
.LBB0_59:
	s_mov_b32 s0, s4
	v_writelane_b32 v255, s0, 13
	v_mbcnt_lo_u32_b32 v0, -1, 0
	v_mbcnt_hi_u32_b32 v0, -1, v0
	s_cmp_eq_u32 s4, 0
	v_add_u32_e32 v2, s6, v0
	v_writelane_b32 v255, s1, 14
	s_movk_i32 s0, 0x84
	v_ashrrev_i32_e32 v4, 1, v2
	s_cselect_b32 s7, s0, 0x80
	v_ashrrev_i32_e32 v5, 31, v4
	s_mul_i32 s0, s7, 22
	v_and_b32_e32 v6, 1, v0
	v_lshlrev_b64 v[2:3], 7, v[4:5]
	s_mov_b32 s1, s45
	s_lshr_b32 s29, s0, 3
	v_lshl_add_u64 v[2:3], s[56:57], 0, v[2:3]
	v_lshlrev_b32_e32 v0, 6, v6
	s_add_i32 s49, s29, 1
	v_lshl_add_u64 v[2:3], v[2:3], 0, v[0:1]
	v_cmp_eq_u32_e64 s[38:39], 0, v6
	v_lshl_add_u32 v0, v4, 2, s84
	s_movk_i32 s12, 0xd000
	v_mov_b64_e32 v[4:5], s[0:1]
	s_mov_b64 s[8:9], s[2:3]
	v_cmp_lt_i32_e32 vcc, v187, v186
	s_nop 1
	v_cndmask_b32_e32 v22, v185, v187, vcc
	v_lshlrev_b32_e32 v22, 2, v22
	s_waitcnt lgkmcnt(0)
	s_cmp_lt_i32 s8, s0
	s_cselect_b32 s15, s8, s2
	s_ashr_i32 s10, s15, 31
	s_lshr_b32 s10, s10, 29
	s_add_i32 s10, s15, s10
	s_ashr_i32 s11, s10, 3
	s_and_b32 s10, s10, -8
	s_sub_i32 s10, s15, s10
	s_cmp_lt_i32 s10, 0
	s_cselect_b32 s13, s49, s29
	s_mul_i32 s10, s13, s10
	s_add_i32 s10, s10, s11
	s_mul_hi_i32 s11, s10, 0x2e8ba2e9
	s_lshr_b32 s13, s11, 31
	s_ashr_i32 s11, s11, 4
	s_add_i32 s11, s11, s13
	s_lshl_b32 s13, s11, 2
	s_sub_i32 s14, s7, s13
	s_min_i32 s14, s14, 4
	s_abs_i32 s14, s14
	v_cvt_f32_u32_e32 v6, s14
	s_sub_i32 s15, 0, s14
	s_mulk_i32 s11, 0x58
	s_sub_i32 s10, s10, s11
	v_rcp_iflag_f32_e32 v6, v6
	s_ashr_i32 s11, s10, 31
	s_abs_i32 s10, s10
	s_nop 0
	v_mul_f32_e32 v6, 0x4f7ffffe, v6
	v_cvt_u32_f32_e32 v6, v6
	s_nop 1
	v_readfirstlane_b32 s16, v6
	s_mul_i32 s15, s15, s16
	s_mul_hi_u32 s15, s16, s15
	s_add_i32 s16, s16, s15
	s_mul_hi_u32 s15, s10, s16
	s_mul_i32 s15, s15, s14
	s_sub_i32 s10, s10, s15
	s_sub_i32 s15, s10, s14
	s_cmp_ge_u32 s10, s14
	s_cselect_b32 s10, s15, s10
	s_sub_i32 s15, s10, s14
	s_cmp_ge_u32 s10, s14
	s_cselect_b32 s10, s15, s10
	s_xor_b32 s10, s10, s11
	s_sub_i32 s10, s10, s11
	s_add_i32 s10, s10, s13
	s_ashr_i32 s11, s10, 31
	s_lshl_b64 s[10:11], s[10:11], 15
	v_lshl_add_u64 v[18:19], v[2:3], 0, s[10:11]
	global_load_dwordx4 v[24:27], v[18:19], off
	global_load_dwordx4 v[28:31], v[18:19], off offset:16
	global_load_dwordx4 v[32:35], v[18:19], off offset:32
	global_load_dwordx4 v[36:39], v[18:19], off offset:48
	s_add_u32 s8, s8, s88
	s_addc_u32 s9, s9, s31
	s_cmp_lt_i32 s8, s0
	s_cselect_b32 s15, s8, s2
	s_ashr_i32 s10, s15, 31
	s_lshr_b32 s10, s10, 29
	s_add_i32 s10, s15, s10
	s_ashr_i32 s11, s10, 3
	s_and_b32 s10, s10, -8
	s_sub_i32 s10, s15, s10
	s_cmp_lt_i32 s10, 0
	s_cselect_b32 s13, s49, s29
	s_mul_i32 s10, s13, s10
	s_add_i32 s10, s10, s11
	s_mul_hi_i32 s11, s10, 0x2e8ba2e9
	s_lshr_b32 s13, s11, 31
	s_ashr_i32 s11, s11, 4
	s_add_i32 s11, s11, s13
	s_lshl_b32 s13, s11, 2
	s_sub_i32 s14, s7, s13
	s_min_i32 s14, s14, 4
	s_abs_i32 s14, s14
	v_cvt_f32_u32_e32 v6, s14
	s_sub_i32 s15, 0, s14
	s_mulk_i32 s11, 0x58
	s_sub_i32 s10, s10, s11
	v_rcp_iflag_f32_e32 v6, v6
	s_ashr_i32 s11, s10, 31
	s_abs_i32 s10, s10
	s_nop 0
	v_mul_f32_e32 v6, 0x4f7ffffe, v6
	v_cvt_u32_f32_e32 v6, v6
	s_nop 1
	v_readfirstlane_b32 s16, v6
	s_mul_i32 s15, s15, s16
	s_mul_hi_u32 s15, s16, s15
	s_add_i32 s16, s16, s15
	s_mul_hi_u32 s15, s10, s16
	s_mul_i32 s15, s15, s14
	s_sub_i32 s10, s10, s15
	s_sub_i32 s15, s10, s14
	s_cmp_ge_u32 s10, s14
	s_cselect_b32 s10, s15, s10
	s_sub_i32 s15, s10, s14
	s_cmp_ge_u32 s10, s14
	s_cselect_b32 s10, s15, s10
	s_xor_b32 s10, s10, s11
	s_sub_i32 s10, s10, s11
	s_add_i32 s10, s10, s13
	s_ashr_i32 s11, s10, 31
	s_lshl_b64 s[10:11], s[10:11], 15
	v_lshl_add_u64 v[18:19], v[2:3], 0, s[10:11]
	global_load_dwordx4 v[40:43], v[18:19], off
	global_load_dwordx4 v[44:47], v[18:19], off offset:16
	global_load_dwordx4 v[48:51], v[18:19], off offset:32
	global_load_dwordx4 v[52:55], v[18:19], off offset:48
	s_add_u32 s8, s8, s88
	s_addc_u32 s9, s9, s31
	s_cmp_lt_i32 s8, s0
	s_cselect_b32 s15, s8, s2
	s_ashr_i32 s10, s15, 31
	s_lshr_b32 s10, s10, 29
	s_add_i32 s10, s15, s10
	s_ashr_i32 s11, s10, 3
	s_and_b32 s10, s10, -8
	s_sub_i32 s10, s15, s10
	s_cmp_lt_i32 s10, 0
	s_cselect_b32 s13, s49, s29
	s_mul_i32 s10, s13, s10
	s_add_i32 s10, s10, s11
	s_mul_hi_i32 s11, s10, 0x2e8ba2e9
	s_lshr_b32 s13, s11, 31
	s_ashr_i32 s11, s11, 4
	s_add_i32 s11, s11, s13
	s_lshl_b32 s13, s11, 2
	s_sub_i32 s14, s7, s13
	s_min_i32 s14, s14, 4
	s_abs_i32 s14, s14
	v_cvt_f32_u32_e32 v6, s14
	s_sub_i32 s15, 0, s14
	s_mulk_i32 s11, 0x58
	s_sub_i32 s10, s10, s11
	v_rcp_iflag_f32_e32 v6, v6
	s_ashr_i32 s11, s10, 31
	s_abs_i32 s10, s10
	s_nop 0
	v_mul_f32_e32 v6, 0x4f7ffffe, v6
	v_cvt_u32_f32_e32 v6, v6
	s_nop 1
	v_readfirstlane_b32 s16, v6
	s_mul_i32 s15, s15, s16
	s_mul_hi_u32 s15, s16, s15
	s_add_i32 s16, s16, s15
	s_mul_hi_u32 s15, s10, s16
	s_mul_i32 s15, s15, s14
	s_sub_i32 s10, s10, s15
	s_sub_i32 s15, s10, s14
	s_cmp_ge_u32 s10, s14
	s_cselect_b32 s10, s15, s10
	s_sub_i32 s15, s10, s14
	s_cmp_ge_u32 s10, s14
	s_cselect_b32 s10, s15, s10
	s_xor_b32 s10, s10, s11
	s_sub_i32 s10, s10, s11
	s_add_i32 s10, s10, s13
	s_ashr_i32 s11, s10, 31
	s_lshl_b64 s[10:11], s[10:11], 15
	v_lshl_add_u64 v[18:19], v[2:3], 0, s[10:11]
	global_load_dwordx4 v[56:59], v[18:19], off
	global_load_dwordx4 v[60:63], v[18:19], off offset:16
	global_load_dwordx4 v[64:67], v[18:19], off offset:32
	global_load_dwordx4 v[68:71], v[18:19], off offset:48
	s_add_u32 s8, s8, s88
	s_addc_u32 s9, s9, s31
	s_cmp_lt_i32 s8, s0
	s_cselect_b32 s15, s8, s2
	s_ashr_i32 s10, s15, 31
	s_lshr_b32 s10, s10, 29
	s_add_i32 s10, s15, s10
	s_ashr_i32 s11, s10, 3
	s_and_b32 s10, s10, -8
	s_sub_i32 s10, s15, s10
	s_cmp_lt_i32 s10, 0
	s_cselect_b32 s13, s49, s29
; #define LAS __attribute__((address_space(3)))
; __device__ __forceinline__ int lane_fresh() { int l; asm volatile("v_mbcnt_lo_u32_b32 %0, -1, 0\n\tv_mbcnt_hi_u32_b32 %0, -1, %0" : "=v"(l)); return l; }
; __device__ __forceinline__ float sum4(f32x4 v) { return (v[0] + v[1]) + (v[2] + v[3]); }
;     __device__ bool next(int i, Unit& u) const {
;         const long L = (long)i * G + c; if (L >= nwg) return false;
;         int wgid = (int)L; { const int q = nwg / NXCD, r = nwg % NXCD, xcd = wgid % NXCD, off = wgid / NXCD; wgid = (xcd < r ? xcd * (q + 1) : r * (q + 1) + (xcd - r) * q) + off; }
;         const int nig = WGM * nN, gid = wgid / nig, fm = gid * WGM, gsz = (nM - fm) < WGM ? (nM - fm) : WGM;
;         u.pm = fm + ((wgid % nig) % gsz); u.pn = (wgid % nig) / gsz; return true;
; template <class Sched>
; __device__ __forceinline__ void run_in_proj(LAS unsigned char* lds, const Params& p, int l, const Sched& S, int M, int rows_off, int wave, int stage_off = -1) {
;     ...
;         const int ln = lane_fresh(), t = wave * 64 + ln, r = t >> 1, hf = t & 1;
;         LAS float* rows = (LAS float*)(lds + rows_off); pg8::Unit u;
;         for (int i = 0; i < 12 && S.next(i, u); ++i) {
;             const f32x4* sp = (const f32x4*)(SSX + ((size_t)u.pm * 256 + r) * 32 + hf * 16);
;             float sm = (sum4(sp[0]) + sum4(sp[1])) + (sum4(sp[2]) + sum4(sp[3]));
	s_mul_i32 s10, s13, s10
	s_add_i32 s10, s10, s11
	s_mul_hi_i32 s11, s10, 0x2e8ba2e9
	s_lshr_b32 s13, s11, 31
	s_ashr_i32 s11, s11, 4
	s_add_i32 s11, s11, s13
	s_lshl_b32 s13, s11, 2
	s_sub_i32 s14, s7, s13
	s_min_i32 s14, s14, 4
	s_abs_i32 s14, s14
	v_cvt_f32_u32_e32 v6, s14
	s_sub_i32 s15, 0, s14
	s_mulk_i32 s11, 0x58
	s_sub_i32 s10, s10, s11
	v_rcp_iflag_f32_e32 v6, v6
	s_ashr_i32 s11, s10, 31
	s_abs_i32 s10, s10
	s_nop 0
	v_mul_f32_e32 v6, 0x4f7ffffe, v6
	v_cvt_u32_f32_e32 v6, v6
	s_nop 1
	v_readfirstlane_b32 s16, v6
	s_mul_i32 s15, s15, s16
	s_mul_hi_u32 s15, s16, s15
	s_add_i32 s16, s16, s15
	s_mul_hi_u32 s15, s10, s16
	s_mul_i32 s15, s15, s14
	s_sub_i32 s10, s10, s15
	s_sub_i32 s15, s10, s14
	s_cmp_ge_u32 s10, s14
	s_cselect_b32 s10, s15, s10
	s_sub_i32 s15, s10, s14
	s_cmp_ge_u32 s10, s14
	s_cselect_b32 s10, s15, s10
	s_xor_b32 s10, s10, s11
	s_sub_i32 s10, s10, s11
	s_add_i32 s10, s10, s13
	s_ashr_i32 s11, s10, 31
	s_lshl_b64 s[10:11], s[10:11], 15
	v_lshl_add_u64 v[18:19], v[2:3], 0, s[10:11]
	global_load_dwordx4 v[72:75], v[18:19], off
	global_load_dwordx4 v[76:79], v[18:19], off offset:16
	global_load_dwordx4 v[80:83], v[18:19], off offset:32
	global_load_dwordx4 v[84:87], v[18:19], off offset:48
	s_add_u32 s8, s8, s88
	s_addc_u32 s9, s9, s31
	s_cmp_lt_i32 s8, s0
	s_cselect_b32 s15, s8, s2
	s_ashr_i32 s10, s15, 31
	s_lshr_b32 s10, s10, 29
	s_add_i32 s10, s15, s10
	s_ashr_i32 s11, s10, 3
	s_and_b32 s10, s10, -8
	s_sub_i32 s10, s15, s10
	s_cmp_lt_i32 s10, 0
	s_cselect_b32 s13, s49, s29
	s_mul_i32 s10, s13, s10
	s_add_i32 s10, s10, s11
	s_mul_hi_i32 s11, s10, 0x2e8ba2e9
	s_lshr_b32 s13, s11, 31
	s_ashr_i32 s11, s11, 4
	s_add_i32 s11, s11, s13
	s_lshl_b32 s13, s11, 2
	s_sub_i32 s14, s7, s13
	s_min_i32 s14, s14, 4
	s_abs_i32 s14, s14
	v_cvt_f32_u32_e32 v6, s14
	s_sub_i32 s15, 0, s14
	s_mulk_i32 s11, 0x58
	s_sub_i32 s10, s10, s11
	v_rcp_iflag_f32_e32 v6, v6
	s_ashr_i32 s11, s10, 31
	s_abs_i32 s10, s10
	s_nop 0
	v_mul_f32_e32 v6, 0x4f7ffffe, v6
	v_cvt_u32_f32_e32 v6, v6
	s_nop 1
	v_readfirstlane_b32 s16, v6
	s_mul_i32 s15, s15, s16
	s_mul_hi_u32 s15, s16, s15
	s_add_i32 s16, s16, s15
	s_mul_hi_u32 s15, s10, s16
	s_mul_i32 s15, s15, s14
	s_sub_i32 s10, s10, s15
	s_sub_i32 s15, s10, s14
	s_cmp_ge_u32 s10, s14
	s_cselect_b32 s10, s15, s10
	s_sub_i32 s15, s10, s14
	s_cmp_ge_u32 s10, s14
	s_cselect_b32 s10, s15, s10
	s_xor_b32 s10, s10, s11
	s_sub_i32 s10, s10, s11
	s_add_i32 s10, s10, s13
	s_ashr_i32 s11, s10, 31
	s_lshl_b64 s[10:11], s[10:11], 15
	v_lshl_add_u64 v[18:19], v[2:3], 0, s[10:11]
	global_load_dwordx4 v[88:91], v[18:19], off
	global_load_dwordx4 v[92:95], v[18:19], off offset:16
	global_load_dwordx4 v[96:99], v[18:19], off offset:32
	global_load_dwordx4 v[100:103], v[18:19], off offset:48
	s_add_u32 s8, s8, s88
	s_addc_u32 s9, s9, s31
	s_cmp_lt_i32 s8, s0
	s_cselect_b32 s15, s8, s2
	s_ashr_i32 s10, s15, 31
	s_lshr_b32 s10, s10, 29
	s_add_i32 s10, s15, s10
	s_ashr_i32 s11, s10, 3
	s_and_b32 s10, s10, -8
	s_sub_i32 s10, s15, s10
	s_cmp_lt_i32 s10, 0
	s_cselect_b32 s13, s49, s29
	s_mul_i32 s10, s13, s10
	s_add_i32 s10, s10, s11
	s_mul_hi_i32 s11, s10, 0x2e8ba2e9
	s_lshr_b32 s13, s11, 31
	s_ashr_i32 s11, s11, 4
	s_add_i32 s11, s11, s13
	s_lshl_b32 s13, s11, 2
	s_sub_i32 s14, s7, s13
	s_min_i32 s14, s14, 4
	s_abs_i32 s14, s14
	v_cvt_f32_u32_e32 v6, s14
	s_sub_i32 s15, 0, s14
	s_mulk_i32 s11, 0x58
	s_sub_i32 s10, s10, s11
	v_rcp_iflag_f32_e32 v6, v6
	s_ashr_i32 s11, s10, 31
	s_abs_i32 s10, s10
	s_nop 0
	v_mul_f32_e32 v6, 0x4f7ffffe, v6
	v_cvt_u32_f32_e32 v6, v6
	s_nop 1
	v_readfirstlane_b32 s16, v6
	s_mul_i32 s15, s15, s16
	s_mul_hi_u32 s15, s16, s15
	s_add_i32 s16, s16, s15
	s_mul_hi_u32 s15, s10, s16
	s_mul_i32 s15, s15, s14
	s_sub_i32 s10, s10, s15
	s_sub_i32 s15, s10, s14
	s_cmp_ge_u32 s10, s14
	s_cselect_b32 s10, s15, s10
	s_sub_i32 s15, s10, s14
	s_cmp_ge_u32 s10, s14
	s_cselect_b32 s10, s15, s10
	s_xor_b32 s10, s10, s11
	s_sub_i32 s10, s10, s11
	s_add_i32 s10, s10, s13
	s_ashr_i32 s11, s10, 31
	s_lshl_b64 s[10:11], s[10:11], 15
	v_lshl_add_u64 v[18:19], v[2:3], 0, s[10:11]
	global_load_dwordx4 v[104:107], v[18:19], off
	global_load_dwordx4 v[108:111], v[18:19], off offset:16
	global_load_dwordx4 v[112:115], v[18:19], off offset:32
	global_load_dwordx4 v[116:119], v[18:19], off offset:48
	s_add_u32 s8, s8, s88
	s_addc_u32 s9, s9, s31
	s_cmp_lt_i32 s8, s0
	s_cselect_b32 s15, s8, s2
	s_ashr_i32 s10, s15, 31
	s_lshr_b32 s10, s10, 29
	s_add_i32 s10, s15, s10
	s_ashr_i32 s11, s10, 3
	s_and_b32 s10, s10, -8
	s_sub_i32 s10, s15, s10
	s_cmp_lt_i32 s10, 0
	s_cselect_b32 s13, s49, s29
	s_mul_i32 s10, s13, s10
	s_add_i32 s10, s10, s11
	s_mul_hi_i32 s11, s10, 0x2e8ba2e9
	s_lshr_b32 s13, s11, 31
	s_ashr_i32 s11, s11, 4
	s_add_i32 s11, s11, s13
	s_lshl_b32 s13, s11, 2
	s_sub_i32 s14, s7, s13
	s_min_i32 s14, s14, 4
	s_abs_i32 s14, s14
	v_cvt_f32_u32_e32 v6, s14
	s_sub_i32 s15, 0, s14
	s_mulk_i32 s11, 0x58
	s_sub_i32 s10, s10, s11
	v_rcp_iflag_f32_e32 v6, v6
	s_ashr_i32 s11, s10, 31
	s_abs_i32 s10, s10
	s_nop 0
	v_mul_f32_e32 v6, 0x4f7ffffe, v6
	v_cvt_u32_f32_e32 v6, v6
	s_nop 1
	v_readfirstlane_b32 s16, v6
	s_mul_i32 s15, s15, s16
	s_mul_hi_u32 s15, s16, s15
	s_add_i32 s16, s16, s15
	s_mul_hi_u32 s15, s10, s16
	s_mul_i32 s15, s15, s14
	s_sub_i32 s10, s10, s15
	s_sub_i32 s15, s10, s14
	s_cmp_ge_u32 s10, s14
	s_cselect_b32 s10, s15, s10
	s_sub_i32 s15, s10, s14
	s_cmp_ge_u32 s10, s14
	s_cselect_b32 s10, s15, s10
	s_xor_b32 s10, s10, s11
	s_sub_i32 s10, s10, s11
	s_add_i32 s10, s10, s13
	s_ashr_i32 s11, s10, 31
	s_lshl_b64 s[10:11], s[10:11], 15
	v_lshl_add_u64 v[18:19], v[2:3], 0, s[10:11]
	global_load_dwordx4 v[120:123], v[18:19], off
; #define LAS __attribute__((address_space(3)))
; __device__ __forceinline__ int lane_fresh() { int l; asm volatile("v_mbcnt_lo_u32_b32 %0, -1, 0\n\tv_mbcnt_hi_u32_b32 %0, -1, %0" : "=v"(l)); return l; }
; __device__ __forceinline__ float sum4(f32x4 v) { return (v[0] + v[1]) + (v[2] + v[3]); }
;     __device__ bool next(int i, Unit& u) const {
;         const long L = (long)i * G + c; if (L >= nwg) return false;
;         int wgid = (int)L; { const int q = nwg / NXCD, r = nwg % NXCD, xcd = wgid % NXCD, off = wgid / NXCD; wgid = (xcd < r ? xcd * (q + 1) : r * (q + 1) + (xcd - r) * q) + off; }
;         const int nig = WGM * nN, gid = wgid / nig, fm = gid * WGM, gsz = (nM - fm) < WGM ? (nM - fm) : WGM;
;         u.pm = fm + ((wgid % nig) % gsz); u.pn = (wgid % nig) / gsz; return true;
; template <class Sched>
; __device__ __forceinline__ void run_in_proj(LAS unsigned char* lds, const Params& p, int l, const Sched& S, int M, int rows_off, int wave, int stage_off = -1) {
;     ...
;         const int ln = lane_fresh(), t = wave * 64 + ln, r = t >> 1, hf = t & 1;
;         LAS float* rows = (LAS float*)(lds + rows_off); pg8::Unit u;
;         for (int i = 0; i < 12 && S.next(i, u); ++i) {
;             const f32x4* sp = (const f32x4*)(SSX + ((size_t)u.pm * 256 + r) * 32 + hf * 16);
;             float sm = (sum4(sp[0]) + sum4(sp[1])) + (sum4(sp[2]) + sum4(sp[3]));
	global_load_dwordx4 v[124:127], v[18:19], off offset:16
	global_load_dwordx4 v[128:131], v[18:19], off offset:32
	global_load_dwordx4 v[132:135], v[18:19], off offset:48
	s_add_u32 s8, s8, s88
	s_addc_u32 s9, s9, s31
	s_cmp_lt_i32 s8, s0
	s_cselect_b32 s15, s8, s2
	s_ashr_i32 s10, s15, 31
	s_lshr_b32 s10, s10, 29
	s_add_i32 s10, s15, s10
	s_ashr_i32 s11, s10, 3
	s_and_b32 s10, s10, -8
	s_sub_i32 s10, s15, s10
	s_cmp_lt_i32 s10, 0
	s_cselect_b32 s13, s49, s29
	s_mul_i32 s10, s13, s10
	s_add_i32 s10, s10, s11
	s_mul_hi_i32 s11, s10, 0x2e8ba2e9
	s_lshr_b32 s13, s11, 31
	s_ashr_i32 s11, s11, 4
	s_add_i32 s11, s11, s13
	s_lshl_b32 s13, s11, 2
	s_sub_i32 s14, s7, s13
	s_min_i32 s14, s14, 4
	s_abs_i32 s14, s14
	v_cvt_f32_u32_e32 v6, s14
	s_sub_i32 s15, 0, s14
	s_mulk_i32 s11, 0x58
	s_sub_i32 s10, s10, s11
	v_rcp_iflag_f32_e32 v6, v6
	s_ashr_i32 s11, s10, 31
	s_abs_i32 s10, s10
	s_nop 0
	v_mul_f32_e32 v6, 0x4f7ffffe, v6
	v_cvt_u32_f32_e32 v6, v6
	s_nop 1
	v_readfirstlane_b32 s16, v6
	s_mul_i32 s15, s15, s16
	s_mul_hi_u32 s15, s16, s15
	s_add_i32 s16, s16, s15
	s_mul_hi_u32 s15, s10, s16
	s_mul_i32 s15, s15, s14
	s_sub_i32 s10, s10, s15
	s_sub_i32 s15, s10, s14
	s_cmp_ge_u32 s10, s14
	s_cselect_b32 s10, s15, s10
	s_sub_i32 s15, s10, s14
	s_cmp_ge_u32 s10, s14
	s_cselect_b32 s10, s15, s10
	s_xor_b32 s10, s10, s11
	s_sub_i32 s10, s10, s11
	s_add_i32 s10, s10, s13
	s_ashr_i32 s11, s10, 31
	s_lshl_b64 s[10:11], s[10:11], 15
	v_lshl_add_u64 v[18:19], v[2:3], 0, s[10:11]
	global_load_dwordx4 v[152:155], v[18:19], off
	global_load_dwordx4 v[156:159], v[18:19], off offset:16
	global_load_dwordx4 v[160:163], v[18:19], off offset:32
	global_load_dwordx4 v[164:167], v[18:19], off offset:48
	s_add_u32 s8, s8, s88
	s_addc_u32 s9, s9, s31
	s_cmp_lt_i32 s8, s0
	s_cselect_b32 s15, s8, s2
	s_ashr_i32 s10, s15, 31
	s_lshr_b32 s10, s10, 29
	s_add_i32 s10, s15, s10
	s_ashr_i32 s11, s10, 3
	s_and_b32 s10, s10, -8
	s_sub_i32 s10, s15, s10
	s_cmp_lt_i32 s10, 0
	s_cselect_b32 s13, s49, s29
	s_mul_i32 s10, s13, s10
	s_add_i32 s10, s10, s11
	s_mul_hi_i32 s11, s10, 0x2e8ba2e9
	s_lshr_b32 s13, s11, 31
	s_ashr_i32 s11, s11, 4
	s_add_i32 s11, s11, s13
	s_lshl_b32 s13, s11, 2
	s_sub_i32 s14, s7, s13
	s_min_i32 s14, s14, 4
	s_abs_i32 s14, s14
	v_cvt_f32_u32_e32 v6, s14
	s_sub_i32 s15, 0, s14
	s_mulk_i32 s11, 0x58
	s_sub_i32 s10, s10, s11
	v_rcp_iflag_f32_e32 v6, v6
	s_ashr_i32 s11, s10, 31
	s_abs_i32 s10, s10
	s_nop 0
	v_mul_f32_e32 v6, 0x4f7ffffe, v6
	v_cvt_u32_f32_e32 v6, v6
	s_nop 1
	v_readfirstlane_b32 s16, v6
	s_mul_i32 s15, s15, s16
	s_mul_hi_u32 s15, s16, s15
	s_add_i32 s16, s16, s15
	s_mul_hi_u32 s15, s10, s16
	s_mul_i32 s15, s15, s14
	s_sub_i32 s10, s10, s15
	s_sub_i32 s15, s10, s14
	s_cmp_ge_u32 s10, s14
	s_cselect_b32 s10, s15, s10
	s_sub_i32 s15, s10, s14
	s_cmp_ge_u32 s10, s14
	s_cselect_b32 s10, s15, s10
	s_xor_b32 s10, s10, s11
	s_sub_i32 s10, s10, s11
	s_add_i32 s10, s10, s13
	s_ashr_i32 s11, s10, 31
	s_lshl_b64 s[10:11], s[10:11], 15
	v_lshl_add_u64 v[18:19], v[2:3], 0, s[10:11]
	global_load_dwordx4 v[168:171], v[18:19], off
	global_load_dwordx4 v[172:175], v[18:19], off offset:16
	global_load_dwordx4 v[176:179], v[18:19], off offset:32
	global_load_dwordx4 v[180:183], v[18:19], off offset:48
	s_add_u32 s8, s8, s88
	s_addc_u32 s9, s9, s31
	s_cmp_lt_i32 s8, s0
	s_cselect_b32 s15, s8, s2
	s_ashr_i32 s10, s15, 31
	s_lshr_b32 s10, s10, 29
	s_add_i32 s10, s15, s10
	s_ashr_i32 s11, s10, 3
	s_and_b32 s10, s10, -8
	s_sub_i32 s10, s15, s10
	s_cmp_lt_i32 s10, 0
	s_cselect_b32 s13, s49, s29
	s_mul_i32 s10, s13, s10
	s_add_i32 s10, s10, s11
	s_mul_hi_i32 s11, s10, 0x2e8ba2e9
	s_lshr_b32 s13, s11, 31
	s_ashr_i32 s11, s11, 4
	s_add_i32 s11, s11, s13
	s_lshl_b32 s13, s11, 2
	s_sub_i32 s14, s7, s13
	s_min_i32 s14, s14, 4
	s_abs_i32 s14, s14
	v_cvt_f32_u32_e32 v6, s14
	s_sub_i32 s15, 0, s14
	s_mulk_i32 s11, 0x58
	s_sub_i32 s10, s10, s11
	v_rcp_iflag_f32_e32 v6, v6
	s_ashr_i32 s11, s10, 31
	s_abs_i32 s10, s10
	s_nop 0
	v_mul_f32_e32 v6, 0x4f7ffffe, v6
	v_cvt_u32_f32_e32 v6, v6
	s_nop 1
	v_readfirstlane_b32 s16, v6
	s_mul_i32 s15, s15, s16
	s_mul_hi_u32 s15, s16, s15
	s_add_i32 s16, s16, s15
	s_mul_hi_u32 s15, s10, s16
	s_mul_i32 s15, s15, s14
	s_sub_i32 s10, s10, s15
	s_sub_i32 s15, s10, s14
	s_cmp_ge_u32 s10, s14
	s_cselect_b32 s10, s15, s10
	s_sub_i32 s15, s10, s14
	s_cmp_ge_u32 s10, s14
	s_cselect_b32 s10, s15, s10
	s_xor_b32 s10, s10, s11
	s_sub_i32 s10, s10, s11
	s_add_i32 s10, s10, s13
	s_ashr_i32 s11, s10, 31
	s_lshl_b64 s[10:11], s[10:11], 15
	v_lshl_add_u64 v[18:19], v[2:3], 0, s[10:11]
	global_load_dwordx4 v[192:195], v[18:19], off
	global_load_dwordx4 v[196:199], v[18:19], off offset:16
	global_load_dwordx4 v[200:203], v[18:19], off offset:32
	global_load_dwordx4 v[204:207], v[18:19], off offset:48
	s_add_u32 s8, s8, s88
	s_addc_u32 s9, s9, s31
	s_cmp_lt_i32 s8, s0
	s_cselect_b32 s15, s8, s2
	s_ashr_i32 s10, s15, 31
	s_lshr_b32 s10, s10, 29
	s_add_i32 s10, s15, s10
	s_ashr_i32 s11, s10, 3
	s_and_b32 s10, s10, -8
	s_sub_i32 s10, s15, s10
	s_cmp_lt_i32 s10, 0
	s_cselect_b32 s13, s49, s29
	s_mul_i32 s10, s13, s10
	s_add_i32 s10, s10, s11
	s_mul_hi_i32 s11, s10, 0x2e8ba2e9
	s_lshr_b32 s13, s11, 31
	s_ashr_i32 s11, s11, 4
	s_add_i32 s11, s11, s13
	s_lshl_b32 s13, s11, 2
	s_sub_i32 s14, s7, s13
	s_min_i32 s14, s14, 4
	s_abs_i32 s14, s14
	v_cvt_f32_u32_e32 v6, s14
	s_sub_i32 s15, 0, s14
	s_mulk_i32 s11, 0x58
	s_sub_i32 s10, s10, s11
	v_rcp_iflag_f32_e32 v6, v6
	s_ashr_i32 s11, s10, 31
	s_abs_i32 s10, s10
	s_nop 0
	v_mul_f32_e32 v6, 0x4f7ffffe, v6
	v_cvt_u32_f32_e32 v6, v6
	s_nop 1
	v_readfirstlane_b32 s16, v6
	s_mul_i32 s15, s15, s16
	s_mul_hi_u32 s15, s16, s15
; __device__ __forceinline__ float sum4(f32x4 v) { return (v[0] + v[1]) + (v[2] + v[3]); }
; template <class Sched>
; __device__ __forceinline__ void run_in_proj(LAS unsigned char* lds, const Params& p, int l, const Sched& S, int M, int rows_off, int wave, int stage_off = -1) {
;     ...
;         for (int i = 0; i < 12 && S.next(i, u); ++i) {
;             const f32x4* sp = (const f32x4*)(SSX + ((size_t)u.pm * 256 + r) * 32 + hf * 16);
;             float sm = (sum4(sp[0]) + sum4(sp[1])) + (sum4(sp[2]) + sum4(sp[3]));
;             sm += __shfl_xor(sm, 1);
	s_add_i32 s16, s16, s15
	s_mul_hi_u32 s15, s10, s16
	s_mul_i32 s15, s15, s14
	s_sub_i32 s10, s10, s15
	s_sub_i32 s15, s10, s14
	s_cmp_ge_u32 s10, s14
	s_cselect_b32 s10, s15, s10
	s_sub_i32 s15, s10, s14
	s_cmp_ge_u32 s10, s14
	s_cselect_b32 s10, s15, s10
	s_xor_b32 s10, s10, s11
	s_sub_i32 s10, s10, s11
	s_add_i32 s10, s10, s13
	s_ashr_i32 s11, s10, 31
	s_lshl_b64 s[10:11], s[10:11], 15
	v_lshl_add_u64 v[18:19], v[2:3], 0, s[10:11]
	global_load_dwordx4 v[208:211], v[18:19], off
	global_load_dwordx4 v[212:215], v[18:19], off offset:16
	global_load_dwordx4 v[216:219], v[18:19], off offset:32
	global_load_dwordx4 v[220:223], v[18:19], off offset:48
	s_add_u32 s8, s8, s88
	s_addc_u32 s9, s9, s31
	s_cmp_lt_i32 s8, s0
	s_cselect_b32 s15, s8, s2
	s_ashr_i32 s10, s15, 31
	s_lshr_b32 s10, s10, 29
	s_add_i32 s10, s15, s10
	s_ashr_i32 s11, s10, 3
	s_and_b32 s10, s10, -8
	s_sub_i32 s10, s15, s10
	s_cmp_lt_i32 s10, 0
	s_cselect_b32 s13, s49, s29
	s_mul_i32 s10, s13, s10
	s_add_i32 s10, s10, s11
	s_mul_hi_i32 s11, s10, 0x2e8ba2e9
	s_lshr_b32 s13, s11, 31
	s_ashr_i32 s11, s11, 4
	s_add_i32 s11, s11, s13
	s_lshl_b32 s13, s11, 2
	s_sub_i32 s14, s7, s13
	s_min_i32 s14, s14, 4
	s_abs_i32 s14, s14
	v_cvt_f32_u32_e32 v6, s14
	s_sub_i32 s15, 0, s14
	s_mulk_i32 s11, 0x58
	s_sub_i32 s10, s10, s11
	v_rcp_iflag_f32_e32 v6, v6
	s_ashr_i32 s11, s10, 31
	s_abs_i32 s10, s10
	s_nop 0
	v_mul_f32_e32 v6, 0x4f7ffffe, v6
	v_cvt_u32_f32_e32 v6, v6
	s_nop 1
	v_readfirstlane_b32 s16, v6
	s_mul_i32 s15, s15, s16
	s_mul_hi_u32 s15, s16, s15
	s_add_i32 s16, s16, s15
	s_mul_hi_u32 s15, s10, s16
	s_mul_i32 s15, s15, s14
	s_sub_i32 s10, s10, s15
	s_sub_i32 s15, s10, s14
	s_cmp_ge_u32 s10, s14
	s_cselect_b32 s10, s15, s10
	s_sub_i32 s15, s10, s14
	s_cmp_ge_u32 s10, s14
	s_cselect_b32 s10, s15, s10
	s_xor_b32 s10, s10, s11
	s_sub_i32 s10, s10, s11
	s_add_i32 s10, s10, s13
	s_ashr_i32 s11, s10, 31
	s_lshl_b64 s[10:11], s[10:11], 15
	v_lshl_add_u64 v[18:19], v[2:3], 0, s[10:11]
	global_load_dwordx4 v[224:227], v[18:19], off
	global_load_dwordx4 v[228:231], v[18:19], off offset:16
	global_load_dwordx4 v[232:235], v[18:19], off offset:32
	global_load_dwordx4 v[236:239], v[18:19], off offset:48
	s_add_u32 s8, s8, s88
	s_addc_u32 s9, s9, s31
	s_waitcnt vmcnt(44)
	v_add_f32_e32 v6, v24, v25
	v_add_f32_e32 v7, v26, v27
	v_add_f32_e32 v8, v28, v29
	v_add_f32_e32 v9, v30, v31
	v_add_f32_e32 v10, v32, v33
	v_add_f32_e32 v11, v34, v35
	v_add_f32_e32 v12, v36, v37
	v_add_f32_e32 v13, v38, v39
	v_add_f32_e32 v6, v6, v7
	v_add_f32_e32 v7, v8, v9
	v_add_f32_e32 v8, v10, v11
	v_add_f32_e32 v9, v12, v13
	v_add_f32_e32 v6, v6, v7
	v_add_f32_e32 v7, v8, v9
	v_add_f32_e32 v24, v6, v7
	s_nop 0
	ds_bpermute_b32 v25, v22, v24
	s_waitcnt vmcnt(40)
	v_add_f32_e32 v6, v40, v41
	v_add_f32_e32 v7, v42, v43
	v_add_f32_e32 v8, v44, v45
	v_add_f32_e32 v9, v46, v47
	v_add_f32_e32 v10, v48, v49
	v_add_f32_e32 v11, v50, v51
	v_add_f32_e32 v12, v52, v53
	v_add_f32_e32 v13, v54, v55
	v_add_f32_e32 v6, v6, v7
	v_add_f32_e32 v7, v8, v9
	v_add_f32_e32 v8, v10, v11
	v_add_f32_e32 v9, v12, v13
	v_add_f32_e32 v6, v6, v7
	v_add_f32_e32 v7, v8, v9
	v_add_f32_e32 v40, v6, v7
	s_nop 0
	ds_bpermute_b32 v41, v22, v40
	s_waitcnt vmcnt(36)
	v_add_f32_e32 v6, v56, v57
	v_add_f32_e32 v7, v58, v59
	v_add_f32_e32 v8, v60, v61
	v_add_f32_e32 v9, v62, v63
	v_add_f32_e32 v10, v64, v65
	v_add_f32_e32 v11, v66, v67
	v_add_f32_e32 v12, v68, v69
	v_add_f32_e32 v13, v70, v71
	v_add_f32_e32 v6, v6, v7
	v_add_f32_e32 v7, v8, v9
	v_add_f32_e32 v8, v10, v11
	v_add_f32_e32 v9, v12, v13
	v_add_f32_e32 v6, v6, v7
	v_add_f32_e32 v7, v8, v9
	v_add_f32_e32 v56, v6, v7
	s_nop 0
	ds_bpermute_b32 v57, v22, v56
	s_waitcnt vmcnt(32)
	v_add_f32_e32 v6, v72, v73
	v_add_f32_e32 v7, v74, v75
	v_add_f32_e32 v8, v76, v77
	v_add_f32_e32 v9, v78, v79
	v_add_f32_e32 v10, v80, v81
	v_add_f32_e32 v11, v82, v83
	v_add_f32_e32 v12, v84, v85
	v_add_f32_e32 v13, v86, v87
	v_add_f32_e32 v6, v6, v7
	v_add_f32_e32 v7, v8, v9
	v_add_f32_e32 v8, v10, v11
	v_add_f32_e32 v9, v12, v13
	v_add_f32_e32 v6, v6, v7
	v_add_f32_e32 v7, v8, v9
	v_add_f32_e32 v72, v6, v7
	s_nop 0
	ds_bpermute_b32 v73, v22, v72
	s_waitcnt vmcnt(28)
	v_add_f32_e32 v6, v88, v89
	v_add_f32_e32 v7, v90, v91
	v_add_f32_e32 v8, v92, v93
	v_add_f32_e32 v9, v94, v95
	v_add_f32_e32 v10, v96, v97
	v_add_f32_e32 v11, v98, v99
	v_add_f32_e32 v12, v100, v101
	v_add_f32_e32 v13, v102, v103
	v_add_f32_e32 v6, v6, v7
	v_add_f32_e32 v7, v8, v9
	v_add_f32_e32 v8, v10, v11
	v_add_f32_e32 v9, v12, v13
	v_add_f32_e32 v6, v6, v7
	v_add_f32_e32 v7, v8, v9
	v_add_f32_e32 v88, v6, v7
	s_nop 0
	ds_bpermute_b32 v89, v22, v88
	s_waitcnt vmcnt(24)
	v_add_f32_e32 v6, v104, v105
	v_add_f32_e32 v7, v106, v107
	v_add_f32_e32 v8, v108, v109
	v_add_f32_e32 v9, v110, v111
	v_add_f32_e32 v10, v112, v113
	v_add_f32_e32 v11, v114, v115
	v_add_f32_e32 v12, v116, v117
	v_add_f32_e32 v13, v118, v119
	v_add_f32_e32 v6, v6, v7
	v_add_f32_e32 v7, v8, v9
	v_add_f32_e32 v8, v10, v11
	v_add_f32_e32 v9, v12, v13
	v_add_f32_e32 v6, v6, v7
	v_add_f32_e32 v7, v8, v9
	v_add_f32_e32 v104, v6, v7
	s_nop 0
	ds_bpermute_b32 v105, v22, v104
	s_waitcnt vmcnt(20)
	v_add_f32_e32 v6, v120, v121
	v_add_f32_e32 v7, v122, v123
	v_add_f32_e32 v8, v124, v125
	v_add_f32_e32 v9, v126, v127
	v_add_f32_e32 v10, v128, v129
	v_add_f32_e32 v11, v130, v131
	v_add_f32_e32 v12, v132, v133
	v_add_f32_e32 v13, v134, v135
	v_add_f32_e32 v6, v6, v7
	v_add_f32_e32 v7, v8, v9
	v_add_f32_e32 v8, v10, v11
	v_add_f32_e32 v9, v12, v13
	v_add_f32_e32 v6, v6, v7
	v_add_f32_e32 v7, v8, v9
	v_add_f32_e32 v120, v6, v7
	s_nop 0
	ds_bpermute_b32 v121, v22, v120
	s_waitcnt vmcnt(16)
; __device__ __forceinline__ float sum4(f32x4 v) { return (v[0] + v[1]) + (v[2] + v[3]); }
; template <class Epi, class Sched>
; __device__ __forceinline__ void gemm_phase(LAS unsigned char* lds, const Gemm g, const Sched& S, const Epi& E, const int wid) {
;     ...
;     if (!S.next(0, cur)) return;
; template <class Sched>
; __device__ __forceinline__ void run_in_proj(LAS unsigned char* lds, const Params& p, int l, const Sched& S, int M, int rows_off, int wave, int stage_off = -1) {
;     ...
;             const f32x4* sp = (const f32x4*)(SSX + ((size_t)u.pm * 256 + r) * 32 + hf * 16);
;             float sm = (sum4(sp[0]) + sum4(sp[1])) + (sum4(sp[2]) + sum4(sp[3]));
;             sm += __shfl_xor(sm, 1);
;             if (hf == 0) rows[i * 256 + r] = __builtin_amdgcn_rsqf(sm * (1.0f / 2048.0f) + EPS);
;         }
;         __syncthreads();
	v_add_f32_e32 v6, v152, v153
	v_add_f32_e32 v7, v154, v155
	v_add_f32_e32 v8, v156, v157
	v_add_f32_e32 v9, v158, v159
	v_add_f32_e32 v10, v160, v161
	v_add_f32_e32 v11, v162, v163
	v_add_f32_e32 v12, v164, v165
	v_add_f32_e32 v13, v166, v167
	v_add_f32_e32 v6, v6, v7
	v_add_f32_e32 v7, v8, v9
	v_add_f32_e32 v8, v10, v11
	v_add_f32_e32 v9, v12, v13
	v_add_f32_e32 v6, v6, v7
	v_add_f32_e32 v7, v8, v9
	v_add_f32_e32 v152, v6, v7
	s_nop 0
	ds_bpermute_b32 v153, v22, v152
	s_waitcnt vmcnt(12)
	v_add_f32_e32 v6, v168, v169
	v_add_f32_e32 v7, v170, v171
	v_add_f32_e32 v8, v172, v173
	v_add_f32_e32 v9, v174, v175
	v_add_f32_e32 v10, v176, v177
	v_add_f32_e32 v11, v178, v179
	v_add_f32_e32 v12, v180, v181
	v_add_f32_e32 v13, v182, v183
	v_add_f32_e32 v6, v6, v7
	v_add_f32_e32 v7, v8, v9
	v_add_f32_e32 v8, v10, v11
	v_add_f32_e32 v9, v12, v13
	v_add_f32_e32 v6, v6, v7
	v_add_f32_e32 v7, v8, v9
	v_add_f32_e32 v168, v6, v7
	s_nop 0
	ds_bpermute_b32 v169, v22, v168
	s_waitcnt vmcnt(8)
	v_add_f32_e32 v6, v192, v193
	v_add_f32_e32 v7, v194, v195
	v_add_f32_e32 v8, v196, v197
	v_add_f32_e32 v9, v198, v199
	v_add_f32_e32 v10, v200, v201
	v_add_f32_e32 v11, v202, v203
	v_add_f32_e32 v12, v204, v205
	v_add_f32_e32 v13, v206, v207
	v_add_f32_e32 v6, v6, v7
	v_add_f32_e32 v7, v8, v9
	v_add_f32_e32 v8, v10, v11
	v_add_f32_e32 v9, v12, v13
	v_add_f32_e32 v6, v6, v7
	v_add_f32_e32 v7, v8, v9
	v_add_f32_e32 v192, v6, v7
	s_nop 0
	ds_bpermute_b32 v193, v22, v192
	s_waitcnt vmcnt(4)
	v_add_f32_e32 v6, v208, v209
	v_add_f32_e32 v7, v210, v211
	v_add_f32_e32 v8, v212, v213
	v_add_f32_e32 v9, v214, v215
	v_add_f32_e32 v10, v216, v217
	v_add_f32_e32 v11, v218, v219
	v_add_f32_e32 v12, v220, v221
	v_add_f32_e32 v13, v222, v223
	v_add_f32_e32 v6, v6, v7
	v_add_f32_e32 v7, v8, v9
	v_add_f32_e32 v8, v10, v11
	v_add_f32_e32 v9, v12, v13
	v_add_f32_e32 v6, v6, v7
	v_add_f32_e32 v7, v8, v9
	v_add_f32_e32 v208, v6, v7
	s_nop 0
	ds_bpermute_b32 v209, v22, v208
	s_waitcnt vmcnt(0)
	v_add_f32_e32 v6, v224, v225
	v_add_f32_e32 v7, v226, v227
	v_add_f32_e32 v8, v228, v229
	v_add_f32_e32 v9, v230, v231
	v_add_f32_e32 v10, v232, v233
	v_add_f32_e32 v11, v234, v235
	v_add_f32_e32 v12, v236, v237
	v_add_f32_e32 v13, v238, v239
	v_add_f32_e32 v6, v6, v7
	v_add_f32_e32 v7, v8, v9
	v_add_f32_e32 v8, v10, v11
	v_add_f32_e32 v9, v12, v13
	v_add_f32_e32 v6, v6, v7
	v_add_f32_e32 v7, v8, v9
	v_add_f32_e32 v224, v6, v7
	s_nop 0
	ds_bpermute_b32 v225, v22, v224
	s_and_saveexec_b64 s[10:11], s[38:39]
	s_cbranch_execz .Lmy_rows1_done
	s_waitcnt lgkmcnt(11)
	v_add_f32_e32 v6, v24, v25
	v_fmamk_f32 v6, v6, 0x3a000000, v184
	v_rsq_f32_e32 v6, v6
	s_nop 0
	ds_write_b32 v0, v6 offset:0
	s_waitcnt lgkmcnt(10)
	v_add_f32_e32 v6, v40, v41
	v_fmamk_f32 v6, v6, 0x3a000000, v184
	v_rsq_f32_e32 v6, v6
	s_nop 0
	ds_write_b32 v0, v6 offset:1024
	s_waitcnt lgkmcnt(9)
	v_add_f32_e32 v6, v56, v57
	v_fmamk_f32 v6, v6, 0x3a000000, v184
	v_rsq_f32_e32 v6, v6
	s_nop 0
	ds_write_b32 v0, v6 offset:2048
	s_waitcnt lgkmcnt(8)
	v_add_f32_e32 v6, v72, v73
	v_fmamk_f32 v6, v6, 0x3a000000, v184
	v_rsq_f32_e32 v6, v6
	s_nop 0
	ds_write_b32 v0, v6 offset:3072
	s_waitcnt lgkmcnt(7)
	v_add_f32_e32 v6, v88, v89
	v_fmamk_f32 v6, v6, 0x3a000000, v184
	v_rsq_f32_e32 v6, v6
	s_nop 0
	ds_write_b32 v0, v6 offset:4096
	s_waitcnt lgkmcnt(6)
	v_add_f32_e32 v6, v104, v105
	v_fmamk_f32 v6, v6, 0x3a000000, v184
	v_rsq_f32_e32 v6, v6
	s_nop 0
	ds_write_b32 v0, v6 offset:5120
	s_waitcnt lgkmcnt(5)
	v_add_f32_e32 v6, v120, v121
	v_fmamk_f32 v6, v6, 0x3a000000, v184
	v_rsq_f32_e32 v6, v6
	s_nop 0
	ds_write_b32 v0, v6 offset:6144
	s_waitcnt lgkmcnt(4)
	v_add_f32_e32 v6, v152, v153
	v_fmamk_f32 v6, v6, 0x3a000000, v184
	v_rsq_f32_e32 v6, v6
	s_nop 0
	ds_write_b32 v0, v6 offset:7168
	s_waitcnt lgkmcnt(3)
	v_add_f32_e32 v6, v168, v169
	v_fmamk_f32 v6, v6, 0x3a000000, v184
	v_rsq_f32_e32 v6, v6
	s_nop 0
	ds_write_b32 v0, v6 offset:8192
	s_waitcnt lgkmcnt(2)
	v_add_f32_e32 v6, v192, v193
	v_fmamk_f32 v6, v6, 0x3a000000, v184
	v_rsq_f32_e32 v6, v6
	s_nop 0
	ds_write_b32 v0, v6 offset:9216
	s_waitcnt lgkmcnt(1)
	v_add_f32_e32 v6, v208, v209
	v_fmamk_f32 v6, v6, 0x3a000000, v184
	v_rsq_f32_e32 v6, v6
	s_nop 0
	ds_write_b32 v0, v6 offset:10240
	s_waitcnt lgkmcnt(0)
	v_add_f32_e32 v6, v224, v225
	v_fmamk_f32 v6, v6, 0x3a000000, v184
	v_rsq_f32_e32 v6, v6
	s_nop 0
	ds_write_b32 v0, v6 offset:11264
.Lmy_rows1_done:
	s_or_b64 exec, exec, s[10:11]
.LBB0_65:
	s_cmp_lt_i32 s2, s0
	s_cselect_b64 s[10:11], -1, 0
	s_cmp_ge_i32 s2, s0
	s_waitcnt lgkmcnt(0)
	s_barrier
	v_mbcnt_lo_u32_b32 v0, -1, 0
	v_mbcnt_hi_u32_b32 v0, -1, v0
	s_cbranch_scc1 .LBB0_67
	v_readlane_b32 s4, v254, 1
	v_readlane_b32 s5, v254, 2
	s_and_b64 s[8:9], s[4:5], exec
	s_cselect_b32 s8, s49, s29
	v_readlane_b32 s4, v254, 3
	s_mul_i32 s8, s8, s4
	v_readlane_b32 s4, v254, 4
	s_add_i32 s8, s8, s4
	s_mul_hi_i32 s9, s8, 0x2e8ba2e9
	s_lshr_b32 s12, s9, 31
	s_ashr_i32 s9, s9, 4
	s_add_i32 s9, s9, s12
	s_lshl_b32 s12, s9, 2
	s_sub_i32 s13, s7, s12
	s_min_i32 s13, s13, 4
	s_abs_i32 s14, s13
	v_cvt_f32_u32_e32 v2, s14
	s_sub_i32 s16, 0, s14
	s_mulk_i32 s9, 0x58
	s_sub_i32 s9, s8, s9
	v_rcp_iflag_f32_e32 v2, v2
	s_abs_i32 s8, s9
	s_xor_b32 s15, s9, s13
	s_ashr_i32 s15, s15, 31
	v_mul_f32_e32 v2, 0x4f7ffffe, v2
	v_cvt_u32_f32_e32 v2, v2
	s_nop 0
	v_readfirstlane_b32 s17, v2
	s_mul_i32 s16, s16, s17
	s_mul_hi_u32 s16, s17, s16
	s_add_i32 s17, s17, s16
	s_mul_hi_u32 s16, s8, s17
	s_mul_i32 s17, s16, s14
	s_sub_i32 s8, s8, s17
	s_add_i32 s18, s16, 1
	s_sub_i32 s17, s8, s14
	s_cmp_ge_u32 s8, s14
	s_cselect_b32 s16, s18, s16
	s_cselect_b32 s8, s17, s8
	s_add_i32 s17, s16, 1
	s_cmp_ge_u32 s8, s14
	s_cselect_b32 s8, s17, s16
	s_xor_b32 s8, s8, s15
	s_sub_i32 s8, s8, s15
	s_mul_i32 s13, s8, s13
	s_sub_i32 s9, s9, s13
	s_add_i32 s46, s12, s9
